# prep solver: forward substitution rewritten with packed f32 FMAs (same summation order) and rolling LDS row prefetch
# baseline (speedup 1.0000x reference)
.LBB0_608:
	s_or_b64 exec, exec, s[0:1]
	s_waitcnt lgkmcnt(0)
	s_barrier
	v_cmp_ne_u32_e32 vcc, v51, v147
	v_lshlrev_b32_e32 v30, 3, v53
	s_and_saveexec_b64 s[0:1], vcc
	s_xor_b64 s[0:1], exec, s[0:1]
	v_lshlrev_b32_e32 v30, 3, v53
	s_andn2_saveexec_b64 s[0:1], s[0:1]
	s_cbranch_execz .LBB0_618
	s_movk_i32 s2, 0x2080
	v_mad_u32_u24 v106, v53, s2, v146
	v_mov_b32_e32 v70, 0
	v_mov_b32_e32 v71, 0
	v_mov_b32_e32 v72, 0
	v_mov_b32_e32 v73, 0
	v_mov_b32_e32 v74, 0
	v_mov_b32_e32 v75, 0
	v_mov_b32_e32 v76, 0
	v_mov_b32_e32 v77, 0
	v_mov_b32_e32 v78, 0
	v_mov_b32_e32 v79, 0
	v_mov_b32_e32 v80, 0
	v_mov_b32_e32 v81, 0
	v_mov_b32_e32 v82, 0
	v_mov_b32_e32 v83, 0
	v_mov_b32_e32 v84, 0
	v_mov_b32_e32 v85, 0
	v_mov_b32_e32 v86, 0
	v_mov_b32_e32 v87, 0
	v_mov_b32_e32 v88, 0
	v_mov_b32_e32 v89, 0
	v_mov_b32_e32 v90, 0
	v_mov_b32_e32 v91, 0
	v_mov_b32_e32 v92, 0
	v_mov_b32_e32 v93, 0
	v_mov_b32_e32 v94, 0
	v_mov_b32_e32 v95, 0
	v_mov_b32_e32 v96, 0
	v_mov_b32_e32 v97, 0
	v_mov_b32_e32 v98, 0
	v_mov_b32_e32 v99, 0
	v_mov_b32_e32 v100, 0
	v_mov_b32_e32 v101, 0
	ds_read_b128 v[2:5], v106 offset:256
	v_cmp_eq_u32_e32 vcc, 0, v52
	s_nop 1
	v_cndmask_b32_e64 v70, 0, 1.0, vcc
	ds_read_b128 v[6:9], v106 offset:512
	s_waitcnt lgkmcnt(1)
	v_pk_mul_f32 v[102:103], v[70:71], v[2:3]
	v_cmp_eq_u32_e32 vcc, 1, v52
	v_add_f32_e32 v68, v102, v103
	s_nop 0
	v_cndmask_b32_e64 v55, 0, 1.0, vcc
	v_sub_f32_e32 v71, v55, v68
	ds_read_b128 v[10:13], v106 offset:768
	s_waitcnt lgkmcnt(1)
	v_pk_mul_f32 v[102:103], v[70:71], v[6:7]
	v_cmp_eq_u32_e32 vcc, 2, v52
	v_add_f32_e32 v68, v102, v103
	s_nop 0
	v_cndmask_b32_e64 v55, 0, 1.0, vcc
	v_sub_f32_e32 v72, v55, v68
	ds_read_b128 v[14:17], v106 offset:1024
	s_waitcnt lgkmcnt(1)
	v_pk_mul_f32 v[102:103], v[70:71], v[10:11]
	v_pk_mul_f32 v[104:105], v[72:73], v[12:13]
	v_cmp_eq_u32_e32 vcc, 3, v52
	v_add_f32_e32 v68, v102, v103
	v_add_f32_e32 v69, v105, v104
	v_cndmask_b32_e64 v55, 0, 1.0, vcc
	v_add_f32_e32 v68, v68, v69
	v_sub_f32_e32 v73, v55, v68
	ds_read_b128 v[18:21], v106 offset:1280
	ds_read_b128 v[22:25], v106 offset:1296
	s_waitcnt lgkmcnt(2)
	v_pk_mul_f32 v[102:103], v[70:71], v[14:15]
	v_pk_mul_f32 v[104:105], v[72:73], v[16:17]
	v_cmp_eq_u32_e32 vcc, 4, v52
	v_add_f32_e32 v68, v102, v103
	v_add_f32_e32 v69, v105, v104
	v_cndmask_b32_e64 v55, 0, 1.0, vcc
	v_add_f32_e32 v68, v68, v69
	v_sub_f32_e32 v74, v55, v68
	ds_read_b128 v[26:29], v106 offset:1536
	ds_read_b128 v[32:35], v106 offset:1552
	s_waitcnt lgkmcnt(3)
	v_pk_mul_f32 v[102:103], v[70:71], v[18:19]
	v_pk_mul_f32 v[104:105], v[72:73], v[20:21]
	s_waitcnt lgkmcnt(2)
	v_pk_fma_f32 v[102:103], v[74:75], v[22:23], v[102:103]
	v_cmp_eq_u32_e32 vcc, 5, v52
	v_add_f32_e32 v68, v102, v103
	v_add_f32_e32 v69, v105, v104
	v_cndmask_b32_e64 v55, 0, 1.0, vcc
	v_add_f32_e32 v68, v68, v69
	v_sub_f32_e32 v75, v55, v68
	ds_read_b128 v[36:39], v106 offset:1792
	ds_read_b128 v[40:43], v106 offset:1808
	s_waitcnt lgkmcnt(3)
	v_pk_mul_f32 v[102:103], v[70:71], v[26:27]
	v_pk_mul_f32 v[104:105], v[72:73], v[28:29]
	s_waitcnt lgkmcnt(2)
	v_pk_fma_f32 v[102:103], v[74:75], v[32:33], v[102:103]
	v_cmp_eq_u32_e32 vcc, 6, v52
	v_add_f32_e32 v68, v102, v103
	v_add_f32_e32 v69, v105, v104
	v_cndmask_b32_e64 v55, 0, 1.0, vcc
	v_add_f32_e32 v68, v68, v69
	v_sub_f32_e32 v76, v55, v68
	ds_read_b128 v[56:59], v106 offset:2048
	ds_read_b128 v[60:63], v106 offset:2064
	s_waitcnt lgkmcnt(3)
	v_pk_mul_f32 v[102:103], v[70:71], v[36:37]
	v_pk_mul_f32 v[104:105], v[72:73], v[38:39]
	s_waitcnt lgkmcnt(2)
	v_pk_fma_f32 v[102:103], v[74:75], v[40:41], v[102:103]
	v_pk_fma_f32 v[104:105], v[76:77], v[42:43], v[104:105]
	v_cmp_eq_u32_e32 vcc, 7, v52
	v_add_f32_e32 v68, v102, v103
	v_add_f32_e32 v69, v105, v104
	v_cndmask_b32_e64 v55, 0, 1.0, vcc
	v_add_f32_e32 v68, v68, v69
	v_sub_f32_e32 v77, v55, v68
	ds_read_b128 v[64:67], v106 offset:2304
	ds_read_b128 v[2:5], v106 offset:2320
	ds_read_b128 v[6:9], v106 offset:2336
	s_waitcnt lgkmcnt(4)
	v_pk_mul_f32 v[102:103], v[70:71], v[56:57]
	v_pk_mul_f32 v[104:105], v[72:73], v[58:59]
	s_waitcnt lgkmcnt(3)
	v_pk_fma_f32 v[102:103], v[74:75], v[60:61], v[102:103]
	v_pk_fma_f32 v[104:105], v[76:77], v[62:63], v[104:105]
	v_cmp_eq_u32_e32 vcc, 8, v52
	v_add_f32_e32 v68, v102, v103
	v_add_f32_e32 v69, v105, v104
	v_cndmask_b32_e64 v55, 0, 1.0, vcc
	v_add_f32_e32 v68, v68, v69
	v_sub_f32_e32 v78, v55, v68
	ds_read_b128 v[10:13], v106 offset:2560
	ds_read_b128 v[14:17], v106 offset:2576
	ds_read_b128 v[18:21], v106 offset:2592
	s_waitcnt lgkmcnt(5)
	v_pk_mul_f32 v[102:103], v[70:71], v[64:65]
	v_pk_mul_f32 v[104:105], v[72:73], v[66:67]
	s_waitcnt lgkmcnt(4)
	v_pk_fma_f32 v[102:103], v[74:75], v[2:3], v[102:103]
	v_pk_fma_f32 v[104:105], v[76:77], v[4:5], v[104:105]
	s_waitcnt lgkmcnt(3)
	v_pk_fma_f32 v[102:103], v[78:79], v[6:7], v[102:103]
	v_cmp_eq_u32_e32 vcc, 9, v52
	v_add_f32_e32 v68, v102, v103
	v_add_f32_e32 v69, v105, v104
	v_cndmask_b32_e64 v55, 0, 1.0, vcc
	v_add_f32_e32 v68, v68, v69
	v_sub_f32_e32 v79, v55, v68
	ds_read_b128 v[22:25], v106 offset:2816
	ds_read_b128 v[26:29], v106 offset:2832
	ds_read_b128 v[32:35], v106 offset:2848
	s_waitcnt lgkmcnt(5)
	v_pk_mul_f32 v[102:103], v[70:71], v[10:11]
	v_pk_mul_f32 v[104:105], v[72:73], v[12:13]
	s_waitcnt lgkmcnt(4)
	v_pk_fma_f32 v[102:103], v[74:75], v[14:15], v[102:103]
	v_pk_fma_f32 v[104:105], v[76:77], v[16:17], v[104:105]
	s_waitcnt lgkmcnt(3)
	v_pk_fma_f32 v[102:103], v[78:79], v[18:19], v[102:103]
	v_cmp_eq_u32_e32 vcc, 10, v52
	v_add_f32_e32 v68, v102, v103
	v_add_f32_e32 v69, v105, v104
	v_cndmask_b32_e64 v55, 0, 1.0, vcc
	v_add_f32_e32 v68, v68, v69
	v_sub_f32_e32 v80, v55, v68
	ds_read_b128 v[36:39], v106 offset:3072
	ds_read_b128 v[40:43], v106 offset:3088
	ds_read_b128 v[56:59], v106 offset:3104
	s_waitcnt lgkmcnt(5)
	v_pk_mul_f32 v[102:103], v[70:71], v[22:23]
	v_pk_mul_f32 v[104:105], v[72:73], v[24:25]
	s_waitcnt lgkmcnt(4)
	v_pk_fma_f32 v[102:103], v[74:75], v[26:27], v[102:103]
	v_pk_fma_f32 v[104:105], v[76:77], v[28:29], v[104:105]
	s_waitcnt lgkmcnt(3)
	v_pk_fma_f32 v[102:103], v[78:79], v[32:33], v[102:103]
	v_pk_fma_f32 v[104:105], v[80:81], v[34:35], v[104:105]
	v_cmp_eq_u32_e32 vcc, 11, v52
	v_add_f32_e32 v68, v102, v103
	v_add_f32_e32 v69, v105, v104
	v_cndmask_b32_e64 v55, 0, 1.0, vcc
	v_add_f32_e32 v68, v68, v69
	v_sub_f32_e32 v81, v55, v68
	ds_read_b128 v[60:63], v106 offset:3328
	ds_read_b128 v[64:67], v106 offset:3344
	ds_read_b128 v[2:5], v106 offset:3360
	ds_read_b128 v[6:9], v106 offset:3376
	s_waitcnt lgkmcnt(6)
	v_pk_mul_f32 v[102:103], v[70:71], v[36:37]
	v_pk_mul_f32 v[104:105], v[72:73], v[38:39]
	s_waitcnt lgkmcnt(5)
	v_pk_fma_f32 v[102:103], v[74:75], v[40:41], v[102:103]
	v_pk_fma_f32 v[104:105], v[76:77], v[42:43], v[104:105]
	s_waitcnt lgkmcnt(4)
	v_pk_fma_f32 v[102:103], v[78:79], v[56:57], v[102:103]
	v_pk_fma_f32 v[104:105], v[80:81], v[58:59], v[104:105]
	v_cmp_eq_u32_e32 vcc, 12, v52
	v_add_f32_e32 v68, v102, v103
	v_add_f32_e32 v69, v105, v104
	v_cndmask_b32_e64 v55, 0, 1.0, vcc
	v_add_f32_e32 v68, v68, v69
	v_sub_f32_e32 v82, v55, v68
	ds_read_b128 v[10:13], v106 offset:3584
	ds_read_b128 v[14:17], v106 offset:3600
	ds_read_b128 v[18:21], v106 offset:3616
	ds_read_b128 v[22:25], v106 offset:3632
	s_waitcnt lgkmcnt(7)
	v_pk_mul_f32 v[102:103], v[70:71], v[60:61]
	v_pk_mul_f32 v[104:105], v[72:73], v[62:63]
	s_waitcnt lgkmcnt(6)
	v_pk_fma_f32 v[102:103], v[74:75], v[64:65], v[102:103]
	v_pk_fma_f32 v[104:105], v[76:77], v[66:67], v[104:105]
	s_waitcnt lgkmcnt(5)
	v_pk_fma_f32 v[102:103], v[78:79], v[2:3], v[102:103]
	v_pk_fma_f32 v[104:105], v[80:81], v[4:5], v[104:105]
	s_waitcnt lgkmcnt(4)
	v_pk_fma_f32 v[102:103], v[82:83], v[6:7], v[102:103]
	v_cmp_eq_u32_e32 vcc, 13, v52
	v_add_f32_e32 v68, v102, v103
	v_add_f32_e32 v69, v105, v104
	v_cndmask_b32_e64 v55, 0, 1.0, vcc
	v_add_f32_e32 v68, v68, v69
	v_sub_f32_e32 v83, v55, v68
	ds_read_b128 v[26:29], v106 offset:3840
	ds_read_b128 v[32:35], v106 offset:3856
	ds_read_b128 v[36:39], v106 offset:3872
	ds_read_b128 v[40:43], v106 offset:3888
	s_waitcnt lgkmcnt(7)
	v_pk_mul_f32 v[102:103], v[70:71], v[10:11]
	v_pk_mul_f32 v[104:105], v[72:73], v[12:13]
	s_waitcnt lgkmcnt(6)
	v_pk_fma_f32 v[102:103], v[74:75], v[14:15], v[102:103]
	v_pk_fma_f32 v[104:105], v[76:77], v[16:17], v[104:105]
	s_waitcnt lgkmcnt(5)
	v_pk_fma_f32 v[102:103], v[78:79], v[18:19], v[102:103]
	v_pk_fma_f32 v[104:105], v[80:81], v[20:21], v[104:105]
	s_waitcnt lgkmcnt(4)
	v_pk_fma_f32 v[102:103], v[82:83], v[22:23], v[102:103]
	v_cmp_eq_u32_e32 vcc, 14, v52
	v_add_f32_e32 v68, v102, v103
	v_add_f32_e32 v69, v105, v104
	v_cndmask_b32_e64 v55, 0, 1.0, vcc
	v_add_f32_e32 v68, v68, v69
	v_sub_f32_e32 v84, v55, v68
	ds_read_b128 v[56:59], v106 offset:4096
	ds_read_b128 v[60:63], v106 offset:4112
	ds_read_b128 v[64:67], v106 offset:4128
	ds_read_b128 v[2:5], v106 offset:4144
	s_waitcnt lgkmcnt(7)
	v_pk_mul_f32 v[102:103], v[70:71], v[26:27]
	v_pk_mul_f32 v[104:105], v[72:73], v[28:29]
	s_waitcnt lgkmcnt(6)
	v_pk_fma_f32 v[102:103], v[74:75], v[32:33], v[102:103]
	v_pk_fma_f32 v[104:105], v[76:77], v[34:35], v[104:105]
	s_waitcnt lgkmcnt(5)
	v_pk_fma_f32 v[102:103], v[78:79], v[36:37], v[102:103]
	v_pk_fma_f32 v[104:105], v[80:81], v[38:39], v[104:105]
	s_waitcnt lgkmcnt(4)
	v_pk_fma_f32 v[102:103], v[82:83], v[40:41], v[102:103]
	v_pk_fma_f32 v[104:105], v[84:85], v[42:43], v[104:105]
	v_cmp_eq_u32_e32 vcc, 15, v52
	v_add_f32_e32 v68, v102, v103
	v_add_f32_e32 v69, v105, v104
	v_cndmask_b32_e64 v55, 0, 1.0, vcc
	v_add_f32_e32 v68, v68, v69
	v_sub_f32_e32 v85, v55, v68
	ds_read_b128 v[6:9], v106 offset:4352
	ds_read_b128 v[10:13], v106 offset:4368
	ds_read_b128 v[14:17], v106 offset:4384
	ds_read_b128 v[18:21], v106 offset:4400
	ds_read_b128 v[22:25], v106 offset:4416
	s_waitcnt lgkmcnt(8)
	v_pk_mul_f32 v[102:103], v[70:71], v[56:57]
	v_pk_mul_f32 v[104:105], v[72:73], v[58:59]
	s_waitcnt lgkmcnt(7)
	v_pk_fma_f32 v[102:103], v[74:75], v[60:61], v[102:103]
	v_pk_fma_f32 v[104:105], v[76:77], v[62:63], v[104:105]
	s_waitcnt lgkmcnt(6)
	v_pk_fma_f32 v[102:103], v[78:79], v[64:65], v[102:103]
	v_pk_fma_f32 v[104:105], v[80:81], v[66:67], v[104:105]
	s_waitcnt lgkmcnt(5)
	v_pk_fma_f32 v[102:103], v[82:83], v[2:3], v[102:103]
	v_pk_fma_f32 v[104:105], v[84:85], v[4:5], v[104:105]
	v_cmp_eq_u32_e32 vcc, 16, v52
	v_add_f32_e32 v68, v102, v103
	v_add_f32_e32 v69, v105, v104
	v_cndmask_b32_e64 v55, 0, 1.0, vcc
	v_add_f32_e32 v68, v68, v69
	v_sub_f32_e32 v86, v55, v68
	ds_read_b128 v[26:29], v106 offset:4608
	ds_read_b128 v[32:35], v106 offset:4624
	ds_read_b128 v[36:39], v106 offset:4640
	ds_read_b128 v[40:43], v106 offset:4656
	ds_read_b128 v[56:59], v106 offset:4672
	s_waitcnt lgkmcnt(9)
	v_pk_mul_f32 v[102:103], v[70:71], v[6:7]
	v_pk_mul_f32 v[104:105], v[72:73], v[8:9]
	s_waitcnt lgkmcnt(8)
	v_pk_fma_f32 v[102:103], v[74:75], v[10:11], v[102:103]
	v_pk_fma_f32 v[104:105], v[76:77], v[12:13], v[104:105]
	s_waitcnt lgkmcnt(7)
	v_pk_fma_f32 v[102:103], v[78:79], v[14:15], v[102:103]
	v_pk_fma_f32 v[104:105], v[80:81], v[16:17], v[104:105]
	s_waitcnt lgkmcnt(6)
	v_pk_fma_f32 v[102:103], v[82:83], v[18:19], v[102:103]
	v_pk_fma_f32 v[104:105], v[84:85], v[20:21], v[104:105]
	s_waitcnt lgkmcnt(5)
	v_pk_fma_f32 v[102:103], v[86:87], v[22:23], v[102:103]
	v_cmp_eq_u32_e32 vcc, 17, v52
	v_add_f32_e32 v68, v102, v103
	v_add_f32_e32 v69, v105, v104
	v_cndmask_b32_e64 v55, 0, 1.0, vcc
	v_add_f32_e32 v68, v68, v69
	v_sub_f32_e32 v87, v55, v68
	ds_read_b128 v[60:63], v106 offset:4864
	ds_read_b128 v[64:67], v106 offset:4880
	ds_read_b128 v[2:5], v106 offset:4896
	ds_read_b128 v[6:9], v106 offset:4912
	ds_read_b128 v[10:13], v106 offset:4928
	s_waitcnt lgkmcnt(9)
	v_pk_mul_f32 v[102:103], v[70:71], v[26:27]
	v_pk_mul_f32 v[104:105], v[72:73], v[28:29]
	s_waitcnt lgkmcnt(8)
	v_pk_fma_f32 v[102:103], v[74:75], v[32:33], v[102:103]
	v_pk_fma_f32 v[104:105], v[76:77], v[34:35], v[104:105]
	s_waitcnt lgkmcnt(7)
	v_pk_fma_f32 v[102:103], v[78:79], v[36:37], v[102:103]
	v_pk_fma_f32 v[104:105], v[80:81], v[38:39], v[104:105]
	s_waitcnt lgkmcnt(6)
	v_pk_fma_f32 v[102:103], v[82:83], v[40:41], v[102:103]
	v_pk_fma_f32 v[104:105], v[84:85], v[42:43], v[104:105]
	s_waitcnt lgkmcnt(5)
	v_pk_fma_f32 v[102:103], v[86:87], v[56:57], v[102:103]
	v_cmp_eq_u32_e32 vcc, 18, v52
	v_add_f32_e32 v68, v102, v103
	v_add_f32_e32 v69, v105, v104
	v_cndmask_b32_e64 v55, 0, 1.0, vcc
	v_add_f32_e32 v68, v68, v69
	v_sub_f32_e32 v88, v55, v68
	ds_read_b128 v[14:17], v106 offset:5120
	ds_read_b128 v[18:21], v106 offset:5136
	ds_read_b128 v[22:25], v106 offset:5152
	ds_read_b128 v[26:29], v106 offset:5168
	ds_read_b128 v[32:35], v106 offset:5184
	s_waitcnt lgkmcnt(9)
	v_pk_mul_f32 v[102:103], v[70:71], v[60:61]
	v_pk_mul_f32 v[104:105], v[72:73], v[62:63]
	s_waitcnt lgkmcnt(8)
	v_pk_fma_f32 v[102:103], v[74:75], v[64:65], v[102:103]
	v_pk_fma_f32 v[104:105], v[76:77], v[66:67], v[104:105]
	s_waitcnt lgkmcnt(7)
	v_pk_fma_f32 v[102:103], v[78:79], v[2:3], v[102:103]
	v_pk_fma_f32 v[104:105], v[80:81], v[4:5], v[104:105]
	s_waitcnt lgkmcnt(6)
	v_pk_fma_f32 v[102:103], v[82:83], v[6:7], v[102:103]
	v_pk_fma_f32 v[104:105], v[84:85], v[8:9], v[104:105]
	s_waitcnt lgkmcnt(5)
	v_pk_fma_f32 v[102:103], v[86:87], v[10:11], v[102:103]
	v_pk_fma_f32 v[104:105], v[88:89], v[12:13], v[104:105]
	v_cmp_eq_u32_e32 vcc, 19, v52
	v_add_f32_e32 v68, v102, v103
	v_add_f32_e32 v69, v105, v104
	v_cndmask_b32_e64 v55, 0, 1.0, vcc
	v_add_f32_e32 v68, v68, v69
	v_sub_f32_e32 v89, v55, v68
	ds_read_b128 v[36:39], v106 offset:5376
	ds_read_b128 v[40:43], v106 offset:5392
	ds_read_b128 v[56:59], v106 offset:5408
	ds_read_b128 v[60:63], v106 offset:5424
	ds_read_b128 v[64:67], v106 offset:5440
	ds_read_b128 v[2:5], v106 offset:5456
	s_waitcnt lgkmcnt(10)
	v_pk_mul_f32 v[102:103], v[70:71], v[14:15]
	v_pk_mul_f32 v[104:105], v[72:73], v[16:17]
	s_waitcnt lgkmcnt(9)
	v_pk_fma_f32 v[102:103], v[74:75], v[18:19], v[102:103]
	v_pk_fma_f32 v[104:105], v[76:77], v[20:21], v[104:105]
	s_waitcnt lgkmcnt(8)
	v_pk_fma_f32 v[102:103], v[78:79], v[22:23], v[102:103]
	v_pk_fma_f32 v[104:105], v[80:81], v[24:25], v[104:105]
	s_waitcnt lgkmcnt(7)
	v_pk_fma_f32 v[102:103], v[82:83], v[26:27], v[102:103]
	v_pk_fma_f32 v[104:105], v[84:85], v[28:29], v[104:105]
	s_waitcnt lgkmcnt(6)
	v_pk_fma_f32 v[102:103], v[86:87], v[32:33], v[102:103]
	v_pk_fma_f32 v[104:105], v[88:89], v[34:35], v[104:105]
	v_cmp_eq_u32_e32 vcc, 20, v52
	v_add_f32_e32 v68, v102, v103
	v_add_f32_e32 v69, v105, v104
	v_cndmask_b32_e64 v55, 0, 1.0, vcc
	v_add_f32_e32 v68, v68, v69
	v_sub_f32_e32 v90, v55, v68
	ds_read_b128 v[6:9], v106 offset:5632
	ds_read_b128 v[10:13], v106 offset:5648
	ds_read_b128 v[14:17], v106 offset:5664
	ds_read_b128 v[18:21], v106 offset:5680
	ds_read_b128 v[22:25], v106 offset:5696
	ds_read_b128 v[26:29], v106 offset:5712
	s_waitcnt lgkmcnt(11)
	v_pk_mul_f32 v[102:103], v[70:71], v[36:37]
	v_pk_mul_f32 v[104:105], v[72:73], v[38:39]
	s_waitcnt lgkmcnt(10)
	v_pk_fma_f32 v[102:103], v[74:75], v[40:41], v[102:103]
	v_pk_fma_f32 v[104:105], v[76:77], v[42:43], v[104:105]
	s_waitcnt lgkmcnt(9)
	v_pk_fma_f32 v[102:103], v[78:79], v[56:57], v[102:103]
	v_pk_fma_f32 v[104:105], v[80:81], v[58:59], v[104:105]
	s_waitcnt lgkmcnt(8)
	v_pk_fma_f32 v[102:103], v[82:83], v[60:61], v[102:103]
	v_pk_fma_f32 v[104:105], v[84:85], v[62:63], v[104:105]
	s_waitcnt lgkmcnt(7)
	v_pk_fma_f32 v[102:103], v[86:87], v[64:65], v[102:103]
	v_pk_fma_f32 v[104:105], v[88:89], v[66:67], v[104:105]
	s_waitcnt lgkmcnt(6)
	v_pk_fma_f32 v[102:103], v[90:91], v[2:3], v[102:103]
	v_cmp_eq_u32_e32 vcc, 21, v52
	v_add_f32_e32 v68, v102, v103
	v_add_f32_e32 v69, v105, v104
	v_cndmask_b32_e64 v55, 0, 1.0, vcc
	v_add_f32_e32 v68, v68, v69
	v_sub_f32_e32 v91, v55, v68
	ds_read_b128 v[32:35], v106 offset:5888
	ds_read_b128 v[36:39], v106 offset:5904
	ds_read_b128 v[40:43], v106 offset:5920
	ds_read_b128 v[56:59], v106 offset:5936
	ds_read_b128 v[60:63], v106 offset:5952
	ds_read_b128 v[64:67], v106 offset:5968
	s_waitcnt lgkmcnt(11)
	v_pk_mul_f32 v[102:103], v[70:71], v[6:7]
	v_pk_mul_f32 v[104:105], v[72:73], v[8:9]
	s_waitcnt lgkmcnt(10)
	v_pk_fma_f32 v[102:103], v[74:75], v[10:11], v[102:103]
	v_pk_fma_f32 v[104:105], v[76:77], v[12:13], v[104:105]
	s_waitcnt lgkmcnt(9)
	v_pk_fma_f32 v[102:103], v[78:79], v[14:15], v[102:103]
	v_pk_fma_f32 v[104:105], v[80:81], v[16:17], v[104:105]
	s_waitcnt lgkmcnt(8)
	v_pk_fma_f32 v[102:103], v[82:83], v[18:19], v[102:103]
	v_pk_fma_f32 v[104:105], v[84:85], v[20:21], v[104:105]
	s_waitcnt lgkmcnt(7)
	v_pk_fma_f32 v[102:103], v[86:87], v[22:23], v[102:103]
	v_pk_fma_f32 v[104:105], v[88:89], v[24:25], v[104:105]
	s_waitcnt lgkmcnt(6)
	v_pk_fma_f32 v[102:103], v[90:91], v[26:27], v[102:103]
	v_cmp_eq_u32_e32 vcc, 22, v52
	v_add_f32_e32 v68, v102, v103
	v_add_f32_e32 v69, v105, v104
	v_cndmask_b32_e64 v55, 0, 1.0, vcc
	v_add_f32_e32 v68, v68, v69
	v_sub_f32_e32 v92, v55, v68
	ds_read_b128 v[2:5], v106 offset:6144
	ds_read_b128 v[6:9], v106 offset:6160
	ds_read_b128 v[10:13], v106 offset:6176
	ds_read_b128 v[14:17], v106 offset:6192
	ds_read_b128 v[18:21], v106 offset:6208
	ds_read_b128 v[22:25], v106 offset:6224
	s_waitcnt lgkmcnt(11)
	v_pk_mul_f32 v[102:103], v[70:71], v[32:33]
	v_pk_mul_f32 v[104:105], v[72:73], v[34:35]
	s_waitcnt lgkmcnt(10)
	v_pk_fma_f32 v[102:103], v[74:75], v[36:37], v[102:103]
	v_pk_fma_f32 v[104:105], v[76:77], v[38:39], v[104:105]
	s_waitcnt lgkmcnt(9)
	v_pk_fma_f32 v[102:103], v[78:79], v[40:41], v[102:103]
	v_pk_fma_f32 v[104:105], v[80:81], v[42:43], v[104:105]
	s_waitcnt lgkmcnt(8)
	v_pk_fma_f32 v[102:103], v[82:83], v[56:57], v[102:103]
	v_pk_fma_f32 v[104:105], v[84:85], v[58:59], v[104:105]
	s_waitcnt lgkmcnt(7)
	v_pk_fma_f32 v[102:103], v[86:87], v[60:61], v[102:103]
	v_pk_fma_f32 v[104:105], v[88:89], v[62:63], v[104:105]
	s_waitcnt lgkmcnt(6)
	v_pk_fma_f32 v[102:103], v[90:91], v[64:65], v[102:103]
	v_pk_fma_f32 v[104:105], v[92:93], v[66:67], v[104:105]
	v_cmp_eq_u32_e32 vcc, 23, v52
	v_add_f32_e32 v68, v102, v103
	v_add_f32_e32 v69, v105, v104
	v_cndmask_b32_e64 v55, 0, 1.0, vcc
	v_add_f32_e32 v68, v68, v69
	v_sub_f32_e32 v93, v55, v68
	ds_read_b128 v[26:29], v106 offset:6400
	ds_read_b128 v[32:35], v106 offset:6416
	ds_read_b128 v[36:39], v106 offset:6432
	ds_read_b128 v[40:43], v106 offset:6448
	ds_read_b128 v[56:59], v106 offset:6464
	ds_read_b128 v[60:63], v106 offset:6480
	ds_read_b128 v[64:67], v106 offset:6496
	s_waitcnt lgkmcnt(12)
	v_pk_mul_f32 v[102:103], v[70:71], v[2:3]
	v_pk_mul_f32 v[104:105], v[72:73], v[4:5]
	s_waitcnt lgkmcnt(11)
	v_pk_fma_f32 v[102:103], v[74:75], v[6:7], v[102:103]
	v_pk_fma_f32 v[104:105], v[76:77], v[8:9], v[104:105]
	s_waitcnt lgkmcnt(10)
	v_pk_fma_f32 v[102:103], v[78:79], v[10:11], v[102:103]
	v_pk_fma_f32 v[104:105], v[80:81], v[12:13], v[104:105]
	s_waitcnt lgkmcnt(9)
	v_pk_fma_f32 v[102:103], v[82:83], v[14:15], v[102:103]
	v_pk_fma_f32 v[104:105], v[84:85], v[16:17], v[104:105]
	s_waitcnt lgkmcnt(8)
	v_pk_fma_f32 v[102:103], v[86:87], v[18:19], v[102:103]
	v_pk_fma_f32 v[104:105], v[88:89], v[20:21], v[104:105]
	s_waitcnt lgkmcnt(7)
	v_pk_fma_f32 v[102:103], v[90:91], v[22:23], v[102:103]
	v_pk_fma_f32 v[104:105], v[92:93], v[24:25], v[104:105]
	v_cmp_eq_u32_e32 vcc, 24, v52
	v_add_f32_e32 v68, v102, v103
	v_add_f32_e32 v69, v105, v104
	v_cndmask_b32_e64 v55, 0, 1.0, vcc
	v_add_f32_e32 v68, v68, v69
	v_sub_f32_e32 v94, v55, v68
	ds_read_b128 v[2:5], v106 offset:6656
	ds_read_b128 v[6:9], v106 offset:6672
	ds_read_b128 v[10:13], v106 offset:6688
	ds_read_b128 v[14:17], v106 offset:6704
	ds_read_b128 v[18:21], v106 offset:6720
	ds_read_b128 v[22:25], v106 offset:6736
	s_waitcnt lgkmcnt(12)
	v_pk_mul_f32 v[102:103], v[70:71], v[26:27]
	v_pk_mul_f32 v[104:105], v[72:73], v[28:29]
	ds_read_b128 v[26:29], v106 offset:6752
	s_waitcnt lgkmcnt(12)
	v_pk_fma_f32 v[102:103], v[74:75], v[32:33], v[102:103]
	v_pk_fma_f32 v[104:105], v[76:77], v[34:35], v[104:105]
	s_waitcnt lgkmcnt(11)
	v_pk_fma_f32 v[102:103], v[78:79], v[36:37], v[102:103]
	v_pk_fma_f32 v[104:105], v[80:81], v[38:39], v[104:105]
	s_waitcnt lgkmcnt(10)
	v_pk_fma_f32 v[102:103], v[82:83], v[40:41], v[102:103]
	v_pk_fma_f32 v[104:105], v[84:85], v[42:43], v[104:105]
	s_waitcnt lgkmcnt(9)
	v_pk_fma_f32 v[102:103], v[86:87], v[56:57], v[102:103]
	v_pk_fma_f32 v[104:105], v[88:89], v[58:59], v[104:105]
	s_waitcnt lgkmcnt(8)
	v_pk_fma_f32 v[102:103], v[90:91], v[60:61], v[102:103]
	v_pk_fma_f32 v[104:105], v[92:93], v[62:63], v[104:105]
	s_waitcnt lgkmcnt(7)
	v_pk_fma_f32 v[102:103], v[94:95], v[64:65], v[102:103]
	v_cmp_eq_u32_e32 vcc, 25, v52
	v_add_f32_e32 v68, v102, v103
	v_add_f32_e32 v69, v105, v104
	v_cndmask_b32_e64 v55, 0, 1.0, vcc
	v_add_f32_e32 v68, v68, v69
	v_sub_f32_e32 v95, v55, v68
	ds_read_b128 v[32:35], v106 offset:6912
	ds_read_b128 v[36:39], v106 offset:6928
	ds_read_b128 v[40:43], v106 offset:6944
	ds_read_b128 v[56:59], v106 offset:6960
	ds_read_b128 v[60:63], v106 offset:6976
	ds_read_b128 v[64:67], v106 offset:6992
	s_waitcnt lgkmcnt(12)
	v_pk_mul_f32 v[102:103], v[70:71], v[2:3]
	v_pk_mul_f32 v[104:105], v[72:73], v[4:5]
	ds_read_b128 v[2:5], v106 offset:7008
	s_waitcnt lgkmcnt(12)
	v_pk_fma_f32 v[102:103], v[74:75], v[6:7], v[102:103]
	v_pk_fma_f32 v[104:105], v[76:77], v[8:9], v[104:105]
	s_waitcnt lgkmcnt(11)
	v_pk_fma_f32 v[102:103], v[78:79], v[10:11], v[102:103]
	v_pk_fma_f32 v[104:105], v[80:81], v[12:13], v[104:105]
	s_waitcnt lgkmcnt(10)
	v_pk_fma_f32 v[102:103], v[82:83], v[14:15], v[102:103]
	v_pk_fma_f32 v[104:105], v[84:85], v[16:17], v[104:105]
	s_waitcnt lgkmcnt(9)
	v_pk_fma_f32 v[102:103], v[86:87], v[18:19], v[102:103]
	v_pk_fma_f32 v[104:105], v[88:89], v[20:21], v[104:105]
	s_waitcnt lgkmcnt(8)
	v_pk_fma_f32 v[102:103], v[90:91], v[22:23], v[102:103]
	v_pk_fma_f32 v[104:105], v[92:93], v[24:25], v[104:105]
	s_waitcnt lgkmcnt(7)
	v_pk_fma_f32 v[102:103], v[94:95], v[26:27], v[102:103]
	v_cmp_eq_u32_e32 vcc, 26, v52
	v_add_f32_e32 v68, v102, v103
	v_add_f32_e32 v69, v105, v104
	v_cndmask_b32_e64 v55, 0, 1.0, vcc
	v_add_f32_e32 v68, v68, v69
	v_sub_f32_e32 v96, v55, v68
	ds_read_b128 v[6:9], v106 offset:7168
	ds_read_b128 v[10:13], v106 offset:7184
	ds_read_b128 v[14:17], v106 offset:7200
	ds_read_b128 v[18:21], v106 offset:7216
	ds_read_b128 v[22:25], v106 offset:7232
	ds_read_b128 v[26:29], v106 offset:7248
	s_waitcnt lgkmcnt(12)
	v_pk_mul_f32 v[102:103], v[70:71], v[32:33]
	v_pk_mul_f32 v[104:105], v[72:73], v[34:35]
	ds_read_b128 v[32:35], v106 offset:7264
	s_waitcnt lgkmcnt(12)
	v_pk_fma_f32 v[102:103], v[74:75], v[36:37], v[102:103]
	v_pk_fma_f32 v[104:105], v[76:77], v[38:39], v[104:105]
	s_waitcnt lgkmcnt(11)
	v_pk_fma_f32 v[102:103], v[78:79], v[40:41], v[102:103]
	v_pk_fma_f32 v[104:105], v[80:81], v[42:43], v[104:105]
	s_waitcnt lgkmcnt(10)
	v_pk_fma_f32 v[102:103], v[82:83], v[56:57], v[102:103]
	v_pk_fma_f32 v[104:105], v[84:85], v[58:59], v[104:105]
	s_waitcnt lgkmcnt(9)
	v_pk_fma_f32 v[102:103], v[86:87], v[60:61], v[102:103]
	v_pk_fma_f32 v[104:105], v[88:89], v[62:63], v[104:105]
	s_waitcnt lgkmcnt(8)
	v_pk_fma_f32 v[102:103], v[90:91], v[64:65], v[102:103]
	v_pk_fma_f32 v[104:105], v[92:93], v[66:67], v[104:105]
	s_waitcnt lgkmcnt(7)
	v_pk_fma_f32 v[102:103], v[94:95], v[2:3], v[102:103]
	v_pk_fma_f32 v[104:105], v[96:97], v[4:5], v[104:105]
	v_cmp_eq_u32_e32 vcc, 27, v52
	v_add_f32_e32 v68, v102, v103
	v_add_f32_e32 v69, v105, v104
	v_cndmask_b32_e64 v55, 0, 1.0, vcc
	v_add_f32_e32 v68, v68, v69
	v_sub_f32_e32 v97, v55, v68
	ds_read_b128 v[36:39], v106 offset:7424
	ds_read_b128 v[40:43], v106 offset:7440
	ds_read_b128 v[56:59], v106 offset:7456
	ds_read_b128 v[60:63], v106 offset:7472
	ds_read_b128 v[64:67], v106 offset:7488
	ds_read_b128 v[2:5], v106 offset:7504
	s_waitcnt lgkmcnt(12)
	v_pk_mul_f32 v[102:103], v[70:71], v[6:7]
	v_pk_mul_f32 v[104:105], v[72:73], v[8:9]
	ds_read_b128 v[6:9], v106 offset:7520
	s_waitcnt lgkmcnt(12)
	v_pk_fma_f32 v[102:103], v[74:75], v[10:11], v[102:103]
	v_pk_fma_f32 v[104:105], v[76:77], v[12:13], v[104:105]
	ds_read_b128 v[10:13], v106 offset:7536
	s_waitcnt lgkmcnt(12)
	v_pk_fma_f32 v[102:103], v[78:79], v[14:15], v[102:103]
	v_pk_fma_f32 v[104:105], v[80:81], v[16:17], v[104:105]
	s_waitcnt lgkmcnt(11)
	v_pk_fma_f32 v[102:103], v[82:83], v[18:19], v[102:103]
	v_pk_fma_f32 v[104:105], v[84:85], v[20:21], v[104:105]
	s_waitcnt lgkmcnt(10)
	v_pk_fma_f32 v[102:103], v[86:87], v[22:23], v[102:103]
	v_pk_fma_f32 v[104:105], v[88:89], v[24:25], v[104:105]
	s_waitcnt lgkmcnt(9)
	v_pk_fma_f32 v[102:103], v[90:91], v[26:27], v[102:103]
	v_pk_fma_f32 v[104:105], v[92:93], v[28:29], v[104:105]
	s_waitcnt lgkmcnt(8)
	v_pk_fma_f32 v[102:103], v[94:95], v[32:33], v[102:103]
	v_pk_fma_f32 v[104:105], v[96:97], v[34:35], v[104:105]
	v_cmp_eq_u32_e32 vcc, 28, v52
	v_add_f32_e32 v68, v102, v103
	v_add_f32_e32 v69, v105, v104
	v_cndmask_b32_e64 v55, 0, 1.0, vcc
	v_add_f32_e32 v68, v68, v69
	v_sub_f32_e32 v98, v55, v68
	ds_read_b128 v[14:17], v106 offset:7680
	ds_read_b128 v[18:21], v106 offset:7696
	ds_read_b128 v[22:25], v106 offset:7712
	ds_read_b128 v[26:29], v106 offset:7728
	ds_read_b128 v[32:35], v106 offset:7744
	s_waitcnt lgkmcnt(12)
	v_pk_mul_f32 v[102:103], v[70:71], v[36:37]
	v_pk_mul_f32 v[104:105], v[72:73], v[38:39]
	ds_read_b128 v[36:39], v106 offset:7760
	s_waitcnt lgkmcnt(12)
	v_pk_fma_f32 v[102:103], v[74:75], v[40:41], v[102:103]
	v_pk_fma_f32 v[104:105], v[76:77], v[42:43], v[104:105]
	ds_read_b128 v[40:43], v106 offset:7776
	s_waitcnt lgkmcnt(12)
	v_pk_fma_f32 v[102:103], v[78:79], v[56:57], v[102:103]
	v_pk_fma_f32 v[104:105], v[80:81], v[58:59], v[104:105]
	ds_read_b128 v[56:59], v106 offset:7792
	s_waitcnt lgkmcnt(12)
	v_pk_fma_f32 v[102:103], v[82:83], v[60:61], v[102:103]
	v_pk_fma_f32 v[104:105], v[84:85], v[62:63], v[104:105]
	s_waitcnt lgkmcnt(11)
	v_pk_fma_f32 v[102:103], v[86:87], v[64:65], v[102:103]
	v_pk_fma_f32 v[104:105], v[88:89], v[66:67], v[104:105]
	s_waitcnt lgkmcnt(10)
	v_pk_fma_f32 v[102:103], v[90:91], v[2:3], v[102:103]
	v_pk_fma_f32 v[104:105], v[92:93], v[4:5], v[104:105]
	s_waitcnt lgkmcnt(9)
	v_pk_fma_f32 v[102:103], v[94:95], v[6:7], v[102:103]
	v_pk_fma_f32 v[104:105], v[96:97], v[8:9], v[104:105]
	s_waitcnt lgkmcnt(8)
	v_pk_fma_f32 v[102:103], v[98:99], v[10:11], v[102:103]
	v_cmp_eq_u32_e32 vcc, 29, v52
	v_add_f32_e32 v68, v102, v103
	v_add_f32_e32 v69, v105, v104
	v_cndmask_b32_e64 v55, 0, 1.0, vcc
	v_add_f32_e32 v68, v68, v69
	v_sub_f32_e32 v99, v55, v68
	ds_read_b128 v[60:63], v106 offset:7936
	ds_read_b128 v[64:67], v106 offset:7952
	ds_read_b128 v[2:5], v106 offset:7968
	ds_read_b128 v[6:9], v106 offset:7984
	ds_read_b128 v[10:13], v106 offset:8000
	s_waitcnt lgkmcnt(12)
	v_pk_mul_f32 v[102:103], v[70:71], v[14:15]
	v_pk_mul_f32 v[104:105], v[72:73], v[16:17]
	ds_read_b128 v[14:17], v106 offset:8016
	s_waitcnt lgkmcnt(12)
	v_pk_fma_f32 v[102:103], v[74:75], v[18:19], v[102:103]
	v_pk_fma_f32 v[104:105], v[76:77], v[20:21], v[104:105]
	ds_read_b128 v[18:21], v106 offset:8032
	s_waitcnt lgkmcnt(12)
	v_pk_fma_f32 v[102:103], v[78:79], v[22:23], v[102:103]
	v_pk_fma_f32 v[104:105], v[80:81], v[24:25], v[104:105]
	ds_read_b128 v[22:25], v106 offset:8048
	s_waitcnt lgkmcnt(12)
	v_pk_fma_f32 v[102:103], v[82:83], v[26:27], v[102:103]
	v_pk_fma_f32 v[104:105], v[84:85], v[28:29], v[104:105]
	s_waitcnt lgkmcnt(11)
	v_pk_fma_f32 v[102:103], v[86:87], v[32:33], v[102:103]
	v_pk_fma_f32 v[104:105], v[88:89], v[34:35], v[104:105]
	s_waitcnt lgkmcnt(10)
	v_pk_fma_f32 v[102:103], v[90:91], v[36:37], v[102:103]
	v_pk_fma_f32 v[104:105], v[92:93], v[38:39], v[104:105]
	s_waitcnt lgkmcnt(9)
	v_pk_fma_f32 v[102:103], v[94:95], v[40:41], v[102:103]
	v_pk_fma_f32 v[104:105], v[96:97], v[42:43], v[104:105]
	s_waitcnt lgkmcnt(8)
	v_pk_fma_f32 v[102:103], v[98:99], v[56:57], v[102:103]
	v_cmp_eq_u32_e32 vcc, 30, v52
	v_add_f32_e32 v68, v102, v103
	v_add_f32_e32 v69, v105, v104
	v_cndmask_b32_e64 v55, 0, 1.0, vcc
	v_add_f32_e32 v68, v68, v69
	v_sub_f32_e32 v100, v55, v68
	s_waitcnt lgkmcnt(7)
	v_pk_mul_f32 v[102:103], v[70:71], v[60:61]
	v_pk_mul_f32 v[104:105], v[72:73], v[62:63]
	s_waitcnt lgkmcnt(6)
	v_pk_fma_f32 v[102:103], v[74:75], v[64:65], v[102:103]
	v_pk_fma_f32 v[104:105], v[76:77], v[66:67], v[104:105]
	s_waitcnt lgkmcnt(5)
	v_pk_fma_f32 v[102:103], v[78:79], v[2:3], v[102:103]
	v_pk_fma_f32 v[104:105], v[80:81], v[4:5], v[104:105]
	s_waitcnt lgkmcnt(4)
	v_pk_fma_f32 v[102:103], v[82:83], v[6:7], v[102:103]
	v_pk_fma_f32 v[104:105], v[84:85], v[8:9], v[104:105]
	s_waitcnt lgkmcnt(3)
	v_pk_fma_f32 v[102:103], v[86:87], v[10:11], v[102:103]
	v_pk_fma_f32 v[104:105], v[88:89], v[12:13], v[104:105]
	s_waitcnt lgkmcnt(2)
	v_pk_fma_f32 v[102:103], v[90:91], v[14:15], v[102:103]
	v_pk_fma_f32 v[104:105], v[92:93], v[16:17], v[104:105]
	s_waitcnt lgkmcnt(1)
	v_pk_fma_f32 v[102:103], v[94:95], v[18:19], v[102:103]
	v_pk_fma_f32 v[104:105], v[96:97], v[20:21], v[104:105]
	s_waitcnt lgkmcnt(0)
	v_pk_fma_f32 v[102:103], v[98:99], v[22:23], v[102:103]
	v_pk_fma_f32 v[104:105], v[100:101], v[24:25], v[104:105]
	v_cmp_eq_u32_e32 vcc, 31, v52
	v_add_f32_e32 v68, v102, v103
	v_add_f32_e32 v69, v105, v104
	v_cndmask_b32_e64 v55, 0, 1.0, vcc
	v_add_f32_e32 v68, v68, v69
	v_sub_f32_e32 v101, v55, v68
	v_mov_b32_e32 v32, v70
	v_mov_b32_e32 v31, v71
	v_mov_b32_e32 v33, v72
	v_mov_b32_e32 v34, v73
	v_mov_b32_e32 v35, v74
	v_mov_b32_e32 v36, v75
	v_mov_b32_e32 v37, v76
	v_mov_b32_e32 v38, v77
	v_mov_b32_e32 v39, v78
	v_mov_b32_e32 v40, v79
	v_mov_b32_e32 v41, v80
	v_mov_b32_e32 v42, v81
	v_mov_b32_e32 v43, v82
	v_mov_b32_e32 v44, v83
	v_mov_b32_e32 v45, v84
	v_mov_b32_e32 v48, v85
	v_mov_b32_e32 v49, v86
	v_mov_b32_e32 v55, v87
	v_mov_b32_e32 v56, v88
	v_mov_b32_e32 v57, v89
	v_mov_b32_e32 v58, v90
	v_mov_b32_e32 v59, v91
	v_mov_b32_e32 v60, v92
	v_mov_b32_e32 v61, v93
	v_mov_b32_e32 v62, v94
	v_mov_b32_e32 v63, v95
	v_mov_b32_e32 v64, v96
	v_mov_b32_e32 v65, v97
	v_mov_b32_e32 v66, v98
	v_mov_b32_e32 v67, v99
	v_mov_b32_e32 v68, v100
	v_mov_b32_e32 v69, v101
	v_cmp_lt_u32_e32 vcc, 31, v160
	v_mul_u32_u24_e32 v2, 40, v52
	s_and_saveexec_b64 s[22:23], vcc
	s_xor_b64 s[22:23], exec, s[22:23]
	s_cbranch_execz .LBB0_613
	v_cvt_pk_bf16_f32 v2, v32, s0
	v_lshl_add_u32 v3, v52, 1, v146
	ds_write_b16 v3, v2 offset:18944
	v_cvt_pk_bf16_f32 v2, v31, s0
	ds_write_b16 v3, v2 offset:19024
	v_cvt_pk_bf16_f32 v2, v33, s0
	ds_write_b16 v3, v2 offset:19104
	v_cvt_pk_bf16_f32 v2, v34, s0
	ds_write_b16 v3, v2 offset:19184
	v_cvt_pk_bf16_f32 v2, v35, s0
	ds_write_b16 v3, v2 offset:19264
	v_cvt_pk_bf16_f32 v2, v36, s0
	ds_write_b16 v3, v2 offset:19344
	v_cvt_pk_bf16_f32 v2, v37, s0
	ds_write_b16 v3, v2 offset:19424
	v_cvt_pk_bf16_f32 v2, v38, s0
	ds_write_b16 v3, v2 offset:19504
	v_cvt_pk_bf16_f32 v2, v39, s0
	ds_write_b16 v3, v2 offset:19584
	v_cvt_pk_bf16_f32 v2, v40, s0
	ds_write_b16 v3, v2 offset:19664
	v_cvt_pk_bf16_f32 v2, v41, s0
	ds_write_b16 v3, v2 offset:19744
	v_cvt_pk_bf16_f32 v2, v42, s0
	ds_write_b16 v3, v2 offset:19824
	v_cvt_pk_bf16_f32 v2, v43, s0
	ds_write_b16 v3, v2 offset:19904
	v_cvt_pk_bf16_f32 v2, v44, s0
	ds_write_b16 v3, v2 offset:19984
	v_cvt_pk_bf16_f32 v2, v45, s0
	ds_write_b16 v3, v2 offset:20064
	v_cvt_pk_bf16_f32 v2, v48, s0
	ds_write_b16 v3, v2 offset:20144
	v_cvt_pk_bf16_f32 v2, v49, s0
	ds_write_b16 v3, v2 offset:20224
	v_cvt_pk_bf16_f32 v2, v55, s0
	ds_write_b16 v3, v2 offset:20304
	v_cvt_pk_bf16_f32 v2, v56, s0
	ds_write_b16 v3, v2 offset:20384
	v_cvt_pk_bf16_f32 v2, v57, s0
	ds_write_b16 v3, v2 offset:20464
	v_cvt_pk_bf16_f32 v2, v58, s0
	ds_write_b16 v3, v2 offset:20544
	v_cvt_pk_bf16_f32 v2, v59, s0
	ds_write_b16 v3, v2 offset:20624
	v_cvt_pk_bf16_f32 v2, v60, s0
	ds_write_b16 v3, v2 offset:20704
	v_cvt_pk_bf16_f32 v2, v61, s0
	ds_write_b16 v3, v2 offset:20784
	v_cvt_pk_bf16_f32 v2, v62, s0
	ds_write_b16 v3, v2 offset:20864
	v_cvt_pk_bf16_f32 v2, v63, s0
	ds_write_b16 v3, v2 offset:20944
	v_cvt_pk_bf16_f32 v2, v64, s0
	ds_write_b16 v3, v2 offset:21024
	v_cvt_pk_bf16_f32 v2, v65, s0
	ds_write_b16 v3, v2 offset:21104
	v_cvt_pk_bf16_f32 v2, v66, s0
	ds_write_b16 v3, v2 offset:21184
	v_cvt_pk_bf16_f32 v2, v67, s0
	ds_write_b16 v3, v2 offset:21264
	v_cvt_pk_bf16_f32 v2, v68, s0
	ds_write_b16 v3, v2 offset:21344
	v_cvt_pk_bf16_f32 v2, v69, s0
	ds_write_b16 v3, v2 offset:21424
	v_mul_u32_u24_e32 v2, 40, v52
